# P5/P6 start stagger: odd XCDs s_sleep 50 (~1.9 us) late
# baseline (speedup 1.0000x reference)
; #define LAS __attribute__((address_space(3)))
;     DI bool next(int i, Unit& u) const {
;         const long L = (long)i * G + c; if (L >= nwg) return false;
;         int wgid = (int)L; { const int q = nwg / NXCD, r = nwg % NXCD, xcd = wgid % NXCD, off = wgid / NXCD; wgid = (xcd < r ? xcd * (q + 1) : r * (q + 1) + (xcd - r) * q) + off; }
;         const int nig = WGM * nN, gid = wgid / nig, fm = gid * WGM, gsz = (nM - fm) < WGM ? (nM - fm) : WGM;
;         u.pm = fm + ((wgid % nig) % gsz); u.pn = (wgid % nig) / gsz; return true;
; __global__ void __launch_bounds__(512, 2) mega(Params p) {
;     ...
;     if (PH(5)) {
;         pg8::Gemm g; g.A0 = (const bf16_t*)(p.ws + WS_ZG); g.A1 = (const bf16_t*)(p.ws + WS_YB) - 2048; g.B0 = (const bf16_t*)(p.ws + WS_WAT); g.B1 = (const bf16_t*)(p.ws + WS_WBT) - 2048;
;         g.lda = DM; g.ldb = DM; g.M = S; g.N = DM; g.K = 2 * DM; g.ksplit = DM / 64;
;         pg8::StaticOrder so; so.init(g.M, g.N, (int)gridDim.x, (int)blockIdx.x);
;         EpiMergeMid e; e.ws = p.ws;
;         pg8::gemm_phase<EpiMergeMid>((LAS unsigned char*)shm, g, so, e);
.LBB0_431:
	s_or_b64 exec, exec, s[4:5]
	v_cmp_gt_i32_e32 vcc, 6, v0
	v_cmp_lt_i32_e64 s[4:5], 5, v1
	s_and_b64 s[4:5], vcc, s[4:5]
	s_and_saveexec_b64 s[6:7], s[4:5]
	s_cbranch_execz .LBB0_456
	s_bitcmp1_b32 s2, 0
	s_cbranch_scc0 .Lp5_nostag
	s_sleep 50

; #define LAS __attribute__((address_space(3)))
;     DI bool next(int i, Unit& u) const {
;         const long L = (long)i * G + c; if (L >= nwg) return false;
;         int wgid = (int)L; { const int q = nwg / NXCD, r = nwg % NXCD, xcd = wgid % NXCD, off = wgid / NXCD; wgid = (xcd < r ? xcd * (q + 1) : r * (q + 1) + (xcd - r) * q) + off; }
;         const int nig = WGM * nN, gid = wgid / nig, fm = gid * WGM, gsz = (nM - fm) < WGM ? (nM - fm) : WGM;
;         u.pm = fm + ((wgid % nig) % gsz); u.pn = (wgid % nig) / gsz; return true;
; __global__ void __launch_bounds__(512, 2) mega(Params p) {
;     ...
;     if (PH(6)) {
;         pg8::Gemm g; g.A0 = (const bf16_t*)(p.ws + WS_MRG); g.A1 = g.A0; g.B0 = (const bf16_t*)(p.ws + WS_WOT); g.B1 = g.B0;
;         g.lda = DM; g.ldb = DM; g.M = S; g.N = DM; g.K = DM; g.ksplit = DM / 64;
;         pg8::StaticOrder so; so.init(g.M, g.N, (int)gridDim.x, (int)blockIdx.x);
;         EpiOut e; e.ws = p.ws;
;         pg8::gemm_phase<EpiOut>((LAS unsigned char*)shm, g, so, e);
.LBB0_506:
	s_or_b64 exec, exec, s[4:5]
	v_cmp_gt_i32_e32 vcc, 7, v0
	v_cmp_lt_i32_e64 s[4:5], 6, v1
	s_and_b64 s[4:5], vcc, s[4:5]
	s_and_saveexec_b64 s[8:9], s[4:5]
	s_cbranch_execz .LBB0_545
	s_bitcmp1_b32 s2, 0
	s_cbranch_scc0 .Lp6_nostag
	s_sleep 50
